# v51 + QKV GEMM K-loop LDS-DMA staging rebalanced 6/2 -> 4/4 as well (GU, down and QKV loops)
# speedup vs baseline: 1.0122x; 1.0009x over previous
; #define PG8_STAGE(bufoff, gbase, voff) do { _Pragma("unroll") for (int _i = 0; _i < 2; ++_i) \
;         __builtin_amdgcn_global_load_lds((const unsigned*)((const char*)(gbase) + (voff)[_i]), (PG8_LAS unsigned*)(lds + (bufoff) + ldsw + _i * 8192), 16, 0, 0); } while (0)
; #define PG8_WAIT_V(n) asm volatile("s_waitcnt vmcnt(" #n ")" ::: "memory")
; #define PG8_BAR __builtin_amdgcn_s_barrier()
; template <class Epi, class Sched, bool ALIGN_EPI = false, bool SP2 = false>
; __device__ __forceinline__ void gemm_phase(PG8_LAS unsigned char* lds, const Gemm g, const Sched& S, const Epi& E) {
;     ...
;     const int aoff = lds_byte(wr * 64 + fr, fq * 8), boff = lds_byte(wc * 32 + fr, fq * 8);
;     ...
;         PG8_STAGE(PG8_SB(0, 0), cB, voffB); PG8_STAGE(PG8_SB(0, 1), cB + hstep, voffB); PG8_STAGE(PG8_SA(0, 0), cA, voffA); PG8_STAGE(PG8_SA(0, 1), cA + hstep, voffA);
;         if (wr == 1) PG8_BAR;
;         PG8_WAIT_V(2); PG8_BAR;
;         PG8_STAGE(PG8_SB(1, 0), cB + kstep, voffB); PG8_STAGE(PG8_SA(1, 0), cA + kstep, voffA); PG8_STAGE(PG8_SB(1, 1), cB + hstep + kstep, voffB);
;         PG8_WAIT_V(6); PG8_BAR;
.LBB0_231:
	v_and_b32_e32 v143, 15, v14
	v_lshrrev_b32_e32 v14, 1, v14
	v_and_b32_e32 v14, 24, v14
	v_lshlrev_b32_e32 v15, 1, v14
	v_lshlrev_b32_e32 v16, 2, v143
	v_lshl_or_b32 v15, v143, 6, v15
	s_lshl_b32 s11, s10, 13
	v_and_b32_e32 v17, 32, v16
	v_bitop3_b32 v18, v15, s11, v17 bitop3:0xde
	s_lshl_b32 s11, s9, 5
	s_and_b32 s55, s11, 0x60
	s_lshr_b32 s53, s12, 6
	s_lshl_b32 s54, s10, 6
	s_lshl_b32 s9, s55, 7
	s_and_b64 s[12:13], s[94:95], exec
	s_cselect_b32 s57, 0x400, 0
	s_add_i32 m0, s49, 0x18000
	v_lshl_add_u64 v[6:7], v[6:7], 0, s[96:97]
	s_waitcnt vmcnt(2)
	s_barrier
	global_load_lds_dwordx4 v[6:7], off
	v_lshl_add_u64 v[4:5], v[4:5], 0, s[96:97]
	s_add_i32 m0, s49, 0x1a000
	s_add_i32 s58, s49, 0x8000
	s_add_i32 s59, s49, 0xa000
	global_load_lds_dwordx4 v[4:5], off
	s_add_u32 s12, s44, 0x40080
	s_addc_u32 s13, s45, 0
	s_add_i32 m0, s49, 0x1c000
	v_lshl_add_u64 v[0:1], s[12:13], 0, v[132:133]
	global_load_lds_dwordx4 v[0:1], off
	v_lshl_add_u64 v[0:1], s[12:13], 0, v[128:129]
	s_add_i32 m0, s49, 0x1e000
	v_and_b32_e32 v2, 1, v12
	global_load_lds_dwordx4 v[0:1], off
	v_lshlrev_b32_e32 v1, 14, v12
	v_and_b32_e32 v1, 0xffff8000, v1
	v_lshl_add_u32 v1, v11, 11, v1
	v_lshl_or_b32 v1, v2, 6, v1
	s_cmpk_lt_u32 s8, 0x100
	v_lshl_add_u32 v136, v13, 1, v1
	v_lshlrev_b32_e32 v1, 14, v8
	v_bitop3_b32 v145, v15, s9, v17 bitop3:0xde
	s_cselect_b64 s[8:9], -1, 0
	s_lshl_b32 s10, s10, 8
	v_and_b32_e32 v1, 0xffff8000, v1
	s_waitcnt vmcnt(4)
	s_add_i32 s10, s10, 0
	v_lshl_add_u32 v1, v9, 11, v1
	v_and_b32_e32 v2, 1, v8
	v_and_or_b32 v0, s11, 32, v14
	s_add_i32 s10, s10, 0x20000
	v_lshl_or_b32 v1, v2, 6, v1
	s_mov_b32 s56, 0
	v_add_u32_e32 v147, s10, v16
	v_mov_b32_e32 v137, v157
	v_lshl_add_u32 v138, v10, 1, v1
	v_mov_b32_e32 v139, v157
	v_add_u32_e32 v149, 0, v18
	v_lshlrev_b32_e32 v140, 1, v0
	s_barrier
	s_waitcnt vmcnt(0)
	s_branch .LBB0_234

; #define PG8_STAGE(bufoff, gbase, voff) do { _Pragma("unroll") for (int _i = 0; _i < 2; ++_i) \
;         __builtin_amdgcn_global_load_lds((const unsigned*)((const char*)(gbase) + (voff)[_i]), (PG8_LAS unsigned*)(lds + (bufoff) + ldsw + _i * 8192), 16, 0, 0); } while (0)
; #define PG8_LDA(dst, b, h) do { _Pragma("unroll") for (int m = 0; m < 4; ++m) _Pragma("unroll") for (int k = 0; k < 2; ++k) dst[m][k] = *(const PG8_LAS bf16x8*)(lds + PG8_SA(b, h) + aoff + m * 2048 + k * 1024); } while (0)
; #define PG8_LDB(dst, b, h) do { _Pragma("unroll") for (int n = 0; n < 2; ++n) _Pragma("unroll") for (int k = 0; k < 2; ++k) dst[n][k] = *(const PG8_LAS bf16x8*)(lds + PG8_SB(b, h) + boff + n * 2048 + k * 1024); } while (0)
; #define PG8_MMA(ai, bj, At, Bt) do { __builtin_amdgcn_s_setprio(1); _Pragma("unroll") for (int m = 0; m < 4; ++m) _Pragma("unroll") for (int n = 0; n < 2; ++n) _Pragma("unroll") for (int k = 0; k < 2; ++k) \
;         acc[ai][bj][m][n] = __builtin_amdgcn_mfma_f32_16x16x32_bf16(Bt[n][k], At[m][k], acc[ai][bj][m][n], 0, 0, 0); __builtin_amdgcn_s_setprio(0); } while (0)
; #define PG8_WAIT_V(n) asm volatile("s_waitcnt vmcnt(" #n ")" ::: "memory")
; #define PG8_WAIT_L(n) asm volatile("s_waitcnt lgkmcnt(" #n ")" ::: "memory")
; #define PG8_BAR __builtin_amdgcn_s_barrier()
; #define PG8_SCHED __builtin_amdgcn_sched_barrier(0)
; template <class Epi, class Sched, bool ALIGN_EPI = false, bool SP2 = false>
; __device__ __forceinline__ void gemm_phase(PG8_LAS unsigned char* lds, const Gemm g, const Sched& S, const Epi& E) {
;     ...
;             const char* a1 = cA + (size_t)(t + 1) * kstep;
;             const char* a2 = last ? nA : cA + (size_t)(t + 2) * kstep; const char* b2 = last ? nB : cB + (size_t)(t + 2) * kstep;
;             const char* a3 = a2 + kstep; const char* b3 = b2 + kstep;
;             if (last && has_next) S.a_ready(nxt);
;             if constexpr (SP2) {
;             PG8_LDB(B0, 0, 0); PG8_LDB(B1, 0, 1); PG8_SCHED; PG8_LDA(At, 0, 0); PG8_STAGE(PG8_SA(1, 1), a1 + hstep, voffA);
;             PG8_WAIT_V(8); PG8_WAIT_L(0); PG8_BAR; PG8_MMA(0, 0, At, B0); PG8_MMA(0, 1, At, B1); PG8_BAR; PG8_SCHED;
;             PG8_LDA(At, 0, 1); PG8_STAGE(PG8_SB(0, 0), b2, voffB); PG8_STAGE(PG8_SB(0, 1), b2 + hstep, voffB); PG8_STAGE(PG8_SA(0, 0), a2, voffA);
.LBB0_237:
	s_add_u32 s44, s42, 0xfffc0080
	s_addc_u32 s45, s43, -1
	s_add_i32 s63, 0, 0x10000
	s_cmp_eq_u32 s62, 12
	s_cselect_b32 s47, s13, s45
	s_cselect_b32 s46, s19, s44
	v_add_u32_e32 v141, s63, v145
	s_cselect_b32 s45, s11, s61
	s_cselect_b32 s44, s41, s60
	s_add_i32 s66, 0, 0x14000
	ds_read_b128 v[150:153], v141
	ds_read_b128 v[170:173], v141 offset:1024
	ds_read_b128 v[174:177], v141 offset:2048
	ds_read_b128 v[178:181], v141 offset:3072
	v_add_u32_e32 v141, s66, v145
	ds_read_b128 v[182:185], v141
	ds_read_b128 v[186:189], v141 offset:1024
	ds_read_b128 v[190:193], v141 offset:2048
	ds_read_b128 v[194:197], v141 offset:3072
	s_add_u32 s64, s42, 0xfffc0000
	s_addc_u32 s65, s43, -1
	v_lshl_add_u64 v[238:239], s[64:65], 0, v[134:135]
	v_lshl_add_u64 v[240:241], s[64:65], 0, v[130:131]
	v_lshl_add_u64 v[154:155], s[42:43], 0, v[136:137]
	s_mov_b32 m0, s58
	ds_read_b128 v[198:201], v149
	ds_read_b128 v[202:205], v149 offset:1024
	ds_read_b128 v[206:209], v149 offset:2048
	ds_read_b128 v[210:213], v149 offset:3072
	ds_read_b128 v[214:217], v149 offset:4096
	ds_read_b128 v[218:221], v149 offset:5120
	ds_read_b128 v[222:225], v149 offset:6144
	ds_read_b128 v[226:229], v149 offset:7168
	global_load_lds_dwordx4 v[238:239], off
	s_mov_b32 m0, s59
	s_nop 0
	global_load_lds_dwordx4 v[240:241], off
	s_add_i32 m0, s49, 0xc000
	s_nop 0
	global_load_lds_dwordx4 v[154:155], off
	v_lshl_add_u64 v[154:155], s[42:43], 0, v[138:139]
	s_add_i32 m0, s49, 0xe000
	s_nop 0
	global_load_lds_dwordx4 v[154:155], off
	s_waitcnt vmcnt(8)
	s_waitcnt lgkmcnt(0)
	s_barrier
	s_waitcnt lgkmcnt(0)
	v_mfma_f32_16x16x32_bf16 v[124:127], v[150:153], v[198:201], v[124:127]
	v_mfma_f32_16x16x32_bf16 v[120:123], v[174:177], v[198:201], v[120:123]
	v_mfma_f32_16x16x32_bf16 v[108:111], v[150:153], v[206:209], v[108:111]
	v_mfma_f32_16x16x32_bf16 v[104:107], v[174:177], v[206:209], v[104:107]
	v_mfma_f32_16x16x32_bf16 v[96:99], v[150:153], v[214:217], v[96:99]
	v_mfma_f32_16x16x32_bf16 v[88:91], v[174:177], v[214:217], v[88:91]
	v_mfma_f32_16x16x32_bf16 v[80:83], v[150:153], v[222:225], v[80:83]
	v_mfma_f32_16x16x32_bf16 v[72:75], v[174:177], v[222:225], v[72:75]
	v_mfma_f32_16x16x32_bf16 v[124:127], v[170:173], v[202:205], v[124:127]
	v_mfma_f32_16x16x32_bf16 v[120:123], v[178:181], v[202:205], v[120:123]
	v_mfma_f32_16x16x32_bf16 v[108:111], v[170:173], v[210:213], v[108:111]
	v_mfma_f32_16x16x32_bf16 v[104:107], v[178:181], v[210:213], v[104:107]
	v_mfma_f32_16x16x32_bf16 v[96:99], v[170:173], v[218:221], v[96:99]
	v_mfma_f32_16x16x32_bf16 v[88:91], v[178:181], v[218:221], v[88:91]
	v_mfma_f32_16x16x32_bf16 v[80:83], v[170:173], v[226:229], v[80:83]
	v_mfma_f32_16x16x32_bf16 v[72:75], v[178:181], v[226:229], v[72:75]
	v_mfma_f32_16x16x32_bf16 v[116:119], v[182:185], v[198:201], v[116:119]
	v_mfma_f32_16x16x32_bf16 v[112:115], v[190:193], v[198:201], v[112:115]
	v_mfma_f32_16x16x32_bf16 v[100:103], v[182:185], v[206:209], v[100:103]
	v_mfma_f32_16x16x32_bf16 v[92:95], v[190:193], v[206:209], v[92:95]
	v_mfma_f32_16x16x32_bf16 v[84:87], v[182:185], v[214:217], v[84:87]
	v_mfma_f32_16x16x32_bf16 v[76:79], v[190:193], v[214:217], v[76:79]
	v_mfma_f32_16x16x32_bf16 v[68:71], v[182:185], v[222:225], v[68:71]
	v_mfma_f32_16x16x32_bf16 v[64:67], v[190:193], v[222:225], v[64:67]
	v_mfma_f32_16x16x32_bf16 v[116:119], v[186:189], v[202:205], v[116:119]
	v_mfma_f32_16x16x32_bf16 v[112:115], v[194:197], v[202:205], v[112:115]
	v_mfma_f32_16x16x32_bf16 v[100:103], v[186:189], v[210:213], v[100:103]
	v_mfma_f32_16x16x32_bf16 v[92:95], v[194:197], v[210:213], v[92:95]
	v_mfma_f32_16x16x32_bf16 v[84:87], v[186:189], v[218:221], v[84:87]
	v_mfma_f32_16x16x32_bf16 v[76:79], v[194:197], v[218:221], v[76:79]
	v_mfma_f32_16x16x32_bf16 v[68:71], v[186:189], v[226:229], v[68:71]
	v_mfma_f32_16x16x32_bf16 v[64:67], v[194:197], v[226:229], v[64:67]
	s_barrier
	s_add_i32 s63, s63, s34
	v_lshl_add_u64 v[154:155], s[44:45], 0, v[132:133]
	s_mov_b32 m0, s63
	ds_read_b128 v[198:201], v149 offset:16384
	ds_read_b128 v[202:205], v149 offset:17408
	ds_read_b128 v[206:209], v149 offset:18432
	ds_read_b128 v[210:213], v149 offset:19456
	ds_read_b128 v[214:217], v149 offset:20480
	ds_read_b128 v[218:221], v149 offset:21504
	ds_read_b128 v[222:225], v149 offset:22528
	ds_read_b128 v[226:229], v149 offset:23552
	global_load_lds_dwordx4 v[154:155], off
	s_add_i32 m0, s63, 0x2000
	s_add_u32 s64, s44, 0x40000
	v_lshl_add_u64 v[236:237], s[44:45], 0, v[128:129]
	s_addc_u32 s65, s45, 0
	s_add_i32 s63, s66, s34
	global_load_lds_dwordx4 v[236:237], off
	v_lshl_add_u64 v[238:239], s[64:65], 0, v[132:133]
	s_mov_b32 m0, s63
	s_nop 0
	global_load_lds_dwordx4 v[238:239], off
	v_lshl_add_u64 v[238:239], s[64:65], 0, v[128:129]
	s_add_i32 m0, s63, 0x2000
	s_nop 0
	global_load_lds_dwordx4 v[238:239], off
	s_waitcnt vmcnt(6)
	s_waitcnt lgkmcnt(0)
	s_barrier
; #define PG8_STAGE(bufoff, gbase, voff) do { _Pragma("unroll") for (int _i = 0; _i < 2; ++_i) \
;         __builtin_amdgcn_global_load_lds((const unsigned*)((const char*)(gbase) + (voff)[_i]), (PG8_LAS unsigned*)(lds + (bufoff) + ldsw + _i * 8192), 16, 0, 0); } while (0)
; #define PG8_LDA(dst, b, h) do { _Pragma("unroll") for (int m = 0; m < 4; ++m) _Pragma("unroll") for (int k = 0; k < 2; ++k) dst[m][k] = *(const PG8_LAS bf16x8*)(lds + PG8_SA(b, h) + aoff + m * 2048 + k * 1024); } while (0)
; #define PG8_LDB(dst, b, h) do { _Pragma("unroll") for (int n = 0; n < 2; ++n) _Pragma("unroll") for (int k = 0; k < 2; ++k) dst[n][k] = *(const PG8_LAS bf16x8*)(lds + PG8_SB(b, h) + boff + n * 2048 + k * 1024); } while (0)
; #define PG8_MMA(ai, bj, At, Bt) do { __builtin_amdgcn_s_setprio(1); _Pragma("unroll") for (int m = 0; m < 4; ++m) _Pragma("unroll") for (int n = 0; n < 2; ++n) _Pragma("unroll") for (int k = 0; k < 2; ++k) \
;         acc[ai][bj][m][n] = __builtin_amdgcn_mfma_f32_16x16x32_bf16(Bt[n][k], At[m][k], acc[ai][bj][m][n], 0, 0, 0); __builtin_amdgcn_s_setprio(0); } while (0)
; #define PG8_WAIT_V(n) asm volatile("s_waitcnt vmcnt(" #n ")" ::: "memory")
; #define PG8_WAIT_L(n) asm volatile("s_waitcnt lgkmcnt(" #n ")" ::: "memory")
; #define PG8_BAR __builtin_amdgcn_s_barrier()
; #define PG8_SCHED __builtin_amdgcn_sched_barrier(0)
; template <class Epi, class Sched, bool ALIGN_EPI = false, bool SP2 = false>
; __device__ __forceinline__ void gemm_phase(PG8_LAS unsigned char* lds, const Gemm g, const Sched& S, const Epi& E) {
;     ...
;             PG8_WAIT_V(8); PG8_WAIT_L(0); PG8_BAR; PG8_MMA(1, 0, At, B0); PG8_MMA(1, 1, At, B1); PG8_BAR; PG8_SCHED;
;             PG8_LDB(B0, 1, 0); PG8_LDB(B1, 1, 1); PG8_SCHED; PG8_LDA(At, 1, 0); PG8_STAGE(PG8_SA(0, 1), a2 + hstep, voffA);
	s_waitcnt lgkmcnt(0)
	v_mfma_f32_16x16x32_bf16 v[60:63], v[150:153], v[198:201], v[60:63]
	v_mfma_f32_16x16x32_bf16 v[56:59], v[174:177], v[198:201], v[56:59]
	v_mfma_f32_16x16x32_bf16 v[44:47], v[150:153], v[206:209], v[44:47]
	v_mfma_f32_16x16x32_bf16 v[40:43], v[174:177], v[206:209], v[40:43]
	v_mfma_f32_16x16x32_bf16 v[32:35], v[150:153], v[214:217], v[32:35]
	v_mfma_f32_16x16x32_bf16 v[24:27], v[174:177], v[214:217], v[24:27]
	v_mfma_f32_16x16x32_bf16 v[16:19], v[150:153], v[222:225], v[16:19]
	v_mfma_f32_16x16x32_bf16 v[8:11], v[174:177], v[222:225], v[8:11]
	v_mfma_f32_16x16x32_bf16 v[60:63], v[170:173], v[202:205], v[60:63]
	v_mfma_f32_16x16x32_bf16 v[56:59], v[178:181], v[202:205], v[56:59]
	v_mfma_f32_16x16x32_bf16 v[44:47], v[170:173], v[210:213], v[44:47]
	v_mfma_f32_16x16x32_bf16 v[40:43], v[178:181], v[210:213], v[40:43]
	v_mfma_f32_16x16x32_bf16 v[32:35], v[170:173], v[218:221], v[32:35]
	v_mfma_f32_16x16x32_bf16 v[24:27], v[178:181], v[218:221], v[24:27]
	v_mfma_f32_16x16x32_bf16 v[16:19], v[170:173], v[226:229], v[16:19]
	v_mfma_f32_16x16x32_bf16 v[8:11], v[178:181], v[226:229], v[8:11]
	v_mfma_f32_16x16x32_bf16 v[52:55], v[182:185], v[198:201], v[52:55]
	v_mfma_f32_16x16x32_bf16 v[48:51], v[190:193], v[198:201], v[48:51]
	v_mfma_f32_16x16x32_bf16 v[36:39], v[182:185], v[206:209], v[36:39]
	v_mfma_f32_16x16x32_bf16 v[28:31], v[190:193], v[206:209], v[28:31]
	v_mfma_f32_16x16x32_bf16 v[20:23], v[182:185], v[214:217], v[20:23]
	v_mfma_f32_16x16x32_bf16 v[12:15], v[190:193], v[214:217], v[12:15]
	v_mfma_f32_16x16x32_bf16 v[4:7], v[182:185], v[222:225], v[4:7]
	v_mfma_f32_16x16x32_bf16 v[0:3], v[190:193], v[222:225], v[0:3]
	v_mfma_f32_16x16x32_bf16 v[52:55], v[186:189], v[202:205], v[52:55]
	v_mfma_f32_16x16x32_bf16 v[48:51], v[194:197], v[202:205], v[48:51]
	v_mfma_f32_16x16x32_bf16 v[36:39], v[186:189], v[210:213], v[36:39]
	v_mfma_f32_16x16x32_bf16 v[28:31], v[194:197], v[210:213], v[28:31]
	v_mfma_f32_16x16x32_bf16 v[20:23], v[186:189], v[218:221], v[20:23]
	v_mfma_f32_16x16x32_bf16 v[12:15], v[194:197], v[218:221], v[12:15]
	v_mfma_f32_16x16x32_bf16 v[4:7], v[186:189], v[226:229], v[4:7]
	v_mfma_f32_16x16x32_bf16 v[0:3], v[194:197], v[226:229], v[0:3]
	s_barrier
	s_add_i32 s63, 0, 0x18000
	v_add_u32_e32 v141, s63, v145
	s_add_i32 s64, 0, 0x1c000
	ds_read_b128 v[150:153], v141
	ds_read_b128 v[170:173], v141 offset:1024
	ds_read_b128 v[174:177], v141 offset:2048
	ds_read_b128 v[178:181], v141 offset:3072
	v_add_u32_e32 v141, s64, v145
	ds_read_b128 v[182:185], v141
	ds_read_b128 v[186:189], v141 offset:1024
	ds_read_b128 v[190:193], v141 offset:2048
	ds_read_b128 v[194:197], v141 offset:3072
	v_lshl_add_u64 v[238:239], s[46:47], 0, v[134:135]
	v_lshl_add_u64 v[240:241], s[46:47], 0, v[130:131]
	s_add_u32 s46, s46, 0x40000
	s_addc_u32 s47, s47, 0
	s_mov_b32 m0, s49
	v_lshl_add_u64 v[242:243], s[46:47], 0, v[134:135]
	ds_read_b128 v[198:201], v149 offset:32768
	ds_read_b128 v[202:205], v149 offset:33792
	ds_read_b128 v[206:209], v149 offset:34816
	ds_read_b128 v[210:213], v149 offset:35840
	ds_read_b128 v[214:217], v149 offset:36864
	ds_read_b128 v[218:221], v149 offset:37888
	ds_read_b128 v[222:225], v149 offset:38912
	ds_read_b128 v[226:229], v149 offset:39936
	global_load_lds_dwordx4 v[238:239], off
	s_mov_b32 m0, s50
	s_nop 0
	global_load_lds_dwordx4 v[240:241], off
	s_mov_b32 m0, s51
	s_nop 0
	global_load_lds_dwordx4 v[242:243], off
	v_lshl_add_u64 v[242:243], s[46:47], 0, v[130:131]
	s_mov_b32 m0, s52
	s_nop 0
	global_load_lds_dwordx4 v[242:243], off
	s_waitcnt vmcnt(8)
	s_waitcnt lgkmcnt(0)
	s_barrier
; #define PG8_STAGE(bufoff, gbase, voff) do { _Pragma("unroll") for (int _i = 0; _i < 2; ++_i) \
;         __builtin_amdgcn_global_load_lds((const unsigned*)((const char*)(gbase) + (voff)[_i]), (PG8_LAS unsigned*)(lds + (bufoff) + ldsw + _i * 8192), 16, 0, 0); } while (0)
; #define PG8_LDA(dst, b, h) do { _Pragma("unroll") for (int m = 0; m < 4; ++m) _Pragma("unroll") for (int k = 0; k < 2; ++k) dst[m][k] = *(const PG8_LAS bf16x8*)(lds + PG8_SA(b, h) + aoff + m * 2048 + k * 1024); } while (0)
; #define PG8_MMA(ai, bj, At, Bt) do { __builtin_amdgcn_s_setprio(1); _Pragma("unroll") for (int m = 0; m < 4; ++m) _Pragma("unroll") for (int n = 0; n < 2; ++n) _Pragma("unroll") for (int k = 0; k < 2; ++k) \
;         acc[ai][bj][m][n] = __builtin_amdgcn_mfma_f32_16x16x32_bf16(Bt[n][k], At[m][k], acc[ai][bj][m][n], 0, 0, 0); __builtin_amdgcn_s_setprio(0); } while (0)
; #define PG8_WAIT_V(n) asm volatile("s_waitcnt vmcnt(" #n ")" ::: "memory")
; #define PG8_WAIT_L(n) asm volatile("s_waitcnt lgkmcnt(" #n ")" ::: "memory")
; #define PG8_BAR __builtin_amdgcn_s_barrier()
; #define PG8_SCHED __builtin_amdgcn_sched_barrier(0)
; template <class Epi, class Sched, bool ALIGN_EPI = false, bool SP2 = false>
; __device__ __forceinline__ void gemm_phase(PG8_LAS unsigned char* lds, const Gemm g, const Sched& S, const Epi& E) {
;     ...
;         for (int t = 0; t < nt; t += 2) {
;     ...
;             PG8_WAIT_V(8); PG8_WAIT_L(0); PG8_BAR; PG8_MMA(0, 0, At, B0); PG8_MMA(0, 1, At, B1); PG8_BAR; PG8_SCHED;
;             PG8_LDA(At, 1, 1); PG8_STAGE(PG8_SB(1, 0), b3, voffB); PG8_STAGE(PG8_SB(1, 1), b3 + hstep, voffB); PG8_STAGE(PG8_SA(1, 0), a3, voffA);
;             PG8_WAIT_V(8); PG8_WAIT_L(0); PG8_BAR; PG8_MMA(1, 0, At, B0); PG8_MMA(1, 1, At, B1); PG8_BAR; PG8_SCHED;
	s_waitcnt lgkmcnt(0)
	v_mfma_f32_16x16x32_bf16 v[124:127], v[150:153], v[198:201], v[124:127]
	v_mfma_f32_16x16x32_bf16 v[120:123], v[174:177], v[198:201], v[120:123]
	v_mfma_f32_16x16x32_bf16 v[108:111], v[150:153], v[206:209], v[108:111]
	v_mfma_f32_16x16x32_bf16 v[104:107], v[174:177], v[206:209], v[104:107]
	v_mfma_f32_16x16x32_bf16 v[96:99], v[150:153], v[214:217], v[96:99]
	v_mfma_f32_16x16x32_bf16 v[88:91], v[174:177], v[214:217], v[88:91]
	v_mfma_f32_16x16x32_bf16 v[80:83], v[150:153], v[222:225], v[80:83]
	v_mfma_f32_16x16x32_bf16 v[72:75], v[174:177], v[222:225], v[72:75]
	v_mfma_f32_16x16x32_bf16 v[124:127], v[170:173], v[202:205], v[124:127]
	v_mfma_f32_16x16x32_bf16 v[120:123], v[178:181], v[202:205], v[120:123]
	v_mfma_f32_16x16x32_bf16 v[108:111], v[170:173], v[210:213], v[108:111]
	v_mfma_f32_16x16x32_bf16 v[104:107], v[178:181], v[210:213], v[104:107]
	v_mfma_f32_16x16x32_bf16 v[96:99], v[170:173], v[218:221], v[96:99]
	v_mfma_f32_16x16x32_bf16 v[88:91], v[178:181], v[218:221], v[88:91]
	v_mfma_f32_16x16x32_bf16 v[80:83], v[170:173], v[226:229], v[80:83]
	v_mfma_f32_16x16x32_bf16 v[72:75], v[178:181], v[226:229], v[72:75]
	v_mfma_f32_16x16x32_bf16 v[116:119], v[182:185], v[198:201], v[116:119]
	v_mfma_f32_16x16x32_bf16 v[112:115], v[190:193], v[198:201], v[112:115]
	v_mfma_f32_16x16x32_bf16 v[100:103], v[182:185], v[206:209], v[100:103]
	v_mfma_f32_16x16x32_bf16 v[92:95], v[190:193], v[206:209], v[92:95]
	v_mfma_f32_16x16x32_bf16 v[84:87], v[182:185], v[214:217], v[84:87]
	v_mfma_f32_16x16x32_bf16 v[76:79], v[190:193], v[214:217], v[76:79]
	v_mfma_f32_16x16x32_bf16 v[68:71], v[182:185], v[222:225], v[68:71]
	v_mfma_f32_16x16x32_bf16 v[64:67], v[190:193], v[222:225], v[64:67]
	v_mfma_f32_16x16x32_bf16 v[116:119], v[186:189], v[202:205], v[116:119]
	v_mfma_f32_16x16x32_bf16 v[112:115], v[194:197], v[202:205], v[112:115]
	v_mfma_f32_16x16x32_bf16 v[100:103], v[186:189], v[210:213], v[100:103]
	v_mfma_f32_16x16x32_bf16 v[92:95], v[194:197], v[210:213], v[92:95]
	v_mfma_f32_16x16x32_bf16 v[84:87], v[186:189], v[218:221], v[84:87]
	v_mfma_f32_16x16x32_bf16 v[76:79], v[194:197], v[218:221], v[76:79]
	v_mfma_f32_16x16x32_bf16 v[68:71], v[186:189], v[226:229], v[68:71]
	v_mfma_f32_16x16x32_bf16 v[64:67], v[194:197], v[226:229], v[64:67]
	s_barrier
	s_add_i32 s46, s63, s34
	v_lshl_add_u64 v[154:155], v[154:155], 0, s[96:97]
	s_mov_b32 m0, s46
	ds_read_b128 v[198:201], v149 offset:49152
	ds_read_b128 v[202:205], v149 offset:50176
	ds_read_b128 v[206:209], v149 offset:51200
	ds_read_b128 v[210:213], v149 offset:52224
	ds_read_b128 v[214:217], v149 offset:53248
	ds_read_b128 v[218:221], v149 offset:54272
	ds_read_b128 v[222:225], v149 offset:55296
	ds_read_b128 v[226:229], v149 offset:56320
	global_load_lds_dwordx4 v[154:155], off
	s_add_i32 m0, s46, 0x2000
	s_add_u32 s44, s44, 0x40080
	v_lshl_add_u64 v[154:155], v[236:237], 0, s[96:97]
	s_addc_u32 s45, s45, 0
	s_add_i32 s46, s64, s34
	global_load_lds_dwordx4 v[154:155], off
	v_lshl_add_u64 v[154:155], s[44:45], 0, v[132:133]
	s_mov_b32 m0, s46
	s_nop 0
	global_load_lds_dwordx4 v[154:155], off
	v_lshl_add_u64 v[154:155], s[44:45], 0, v[128:129]
	s_add_i32 m0, s46, 0x2000
	s_nop 0
	global_load_lds_dwordx4 v[154:155], off
	s_waitcnt vmcnt(6)
	s_waitcnt lgkmcnt(0)
	s_barrier
	s_waitcnt lgkmcnt(0)
	v_mfma_f32_16x16x32_bf16 v[60:63], v[150:153], v[198:201], v[60:63]
	v_mfma_f32_16x16x32_bf16 v[56:59], v[174:177], v[198:201], v[56:59]
	v_mfma_f32_16x16x32_bf16 v[44:47], v[150:153], v[206:209], v[44:47]
	v_mfma_f32_16x16x32_bf16 v[40:43], v[174:177], v[206:209], v[40:43]
	v_mfma_f32_16x16x32_bf16 v[32:35], v[150:153], v[214:217], v[32:35]
	v_mfma_f32_16x16x32_bf16 v[24:27], v[174:177], v[214:217], v[24:27]
	v_mfma_f32_16x16x32_bf16 v[16:19], v[150:153], v[222:225], v[16:19]
	v_mfma_f32_16x16x32_bf16 v[8:11], v[174:177], v[222:225], v[8:11]
	v_mfma_f32_16x16x32_bf16 v[60:63], v[170:173], v[202:205], v[60:63]
	v_mfma_f32_16x16x32_bf16 v[56:59], v[178:181], v[202:205], v[56:59]
	v_mfma_f32_16x16x32_bf16 v[44:47], v[170:173], v[210:213], v[44:47]
	v_mfma_f32_16x16x32_bf16 v[40:43], v[178:181], v[210:213], v[40:43]
	v_mfma_f32_16x16x32_bf16 v[32:35], v[170:173], v[218:221], v[32:35]
	v_mfma_f32_16x16x32_bf16 v[24:27], v[178:181], v[218:221], v[24:27]
	v_mfma_f32_16x16x32_bf16 v[16:19], v[170:173], v[226:229], v[16:19]
	v_mfma_f32_16x16x32_bf16 v[8:11], v[178:181], v[226:229], v[8:11]
	v_mfma_f32_16x16x32_bf16 v[52:55], v[182:185], v[198:201], v[52:55]
	v_mfma_f32_16x16x32_bf16 v[48:51], v[190:193], v[198:201], v[48:51]
	v_mfma_f32_16x16x32_bf16 v[36:39], v[182:185], v[206:209], v[36:39]
	v_mfma_f32_16x16x32_bf16 v[28:31], v[190:193], v[206:209], v[28:31]
	v_mfma_f32_16x16x32_bf16 v[20:23], v[182:185], v[214:217], v[20:23]
	v_mfma_f32_16x16x32_bf16 v[12:15], v[190:193], v[214:217], v[12:15]
	v_mfma_f32_16x16x32_bf16 v[4:7], v[182:185], v[222:225], v[4:7]
	v_mfma_f32_16x16x32_bf16 v[0:3], v[190:193], v[222:225], v[0:3]
	v_mfma_f32_16x16x32_bf16 v[52:55], v[186:189], v[202:205], v[52:55]
	v_mfma_f32_16x16x32_bf16 v[48:51], v[194:197], v[202:205], v[48:51]
	v_mfma_f32_16x16x32_bf16 v[36:39], v[186:189], v[210:213], v[36:39]
	v_mfma_f32_16x16x32_bf16 v[28:31], v[194:197], v[210:213], v[28:31]
	v_mfma_f32_16x16x32_bf16 v[20:23], v[186:189], v[218:221], v[20:23]
	v_mfma_f32_16x16x32_bf16 v[12:15], v[194:197], v[218:221], v[12:15]
	v_mfma_f32_16x16x32_bf16 v[4:7], v[186:189], v[226:229], v[4:7]
	v_mfma_f32_16x16x32_bf16 v[0:3], v[194:197], v[226:229], v[0:3]
	s_barrier
	s_add_i32 s62, s62, 2
	s_add_u32 s42, s42, 0x100
	s_addc_u32 s43, s43, 0
	s_add_u32 s60, s60, 0x100
	s_addc_u32 s61, s61, 0
	s_cmp_gt_u32 s62, 13
	s_cbranch_scc0 .LBB0_237
	s_and_b64 vcc, exec, s[8:9]
	s_cbranch_vccz .LBB0_240
	s_barrier
